# FoX hot tile body: next tile's K fragments re-loaded into each V-fragment register right after the PV MFMA that read it (rolling LDS prefetch), on top of the MLA rolling prefetch
# speedup vs baseline: 1.0585x; 1.0011x over previous
; #define LAS __attribute__((address_space(3)))
; __device__ __forceinline__ int crow(int r, int hi) { return (r & 3) + 8 * (r >> 2) + 4 * hi; }
; template <int DQK, int DV, bool FOX> ...
;     ...
;             float mloc = mref, cqt = 0.f;
;             if (FOX) {
;                 cqt = cq - __builtin_bit_cast(float, __builtin_amdgcn_readlane(__builtin_bit_cast(int, basev), t));
;                 mloc = mref - cqt;
;                 if (t == ntw - 1) { const int qrel = 32 * (w & 1) + r;
; #pragma unroll
;                     for (int i = 0; i < 16; ++i) { const int kv = crow(i, h); if (kv > qrel) p0[i] = -INFINITY; if (kv + 32 > qrel) p1[i] = -INFINITY; } }
;             }
;             float rm = fmaxf(fmaxf(p0[0], p1[0]), p0[1]);
; #pragma unroll
;             for (int i = 1; i < 15; ++i) rm = fmaxf(fmaxf(rm, p1[i]), p0[i + 1]);
;             rm = fmaxf(rm, p1[15]);
;             { const auto rr_ = __builtin_amdgcn_permlane32_swap(__float_as_uint(rm), __float_as_uint(rm), false, false);
;               rm = fmaxf(__uint_as_float(rr_[0]), __uint_as_float(rr_[1])); }
;             const bool grow = rm > mloc + THR;
;             if (__any(grow)) {
;                 const float mnew = grow ? rm : mloc; const float al = __builtin_amdgcn_exp2f(mloc - mnew);
;                 lsum *= al; mref = grow ? (mnew + cqt) : mref; mloc = mnew;
;                 if (h == 0) wsf[r] = al;
;     ...
;             for (int cb = 0; cb < NCB; ++cb) { s16x4 lo[4], hi[4];
; #pragma unroll
;                 for (int ks = 0; ks < 4; ++ks) {
;                     if (FOX && cb == 0) { lo[ks] = vlo0[ks]; hi[ks] = vhi0[ks]; }
;                     else {
;                     lo[ks] = __builtin_bit_cast(s16x4, __builtin_amdgcn_ds_read_tr16_b64_v4i16((LAS s16x4*)(b + vread0 + cb * 4096 + ks * 1024)));
;                     hi[ks] = __builtin_bit_cast(s16x4, __builtin_amdgcn_ds_read_tr16_b64_v4i16((LAS s16x4*)(b + vread0 + cb * 4096 + ks * 1024 + 512))); } }
;                 __builtin_amdgcn_sched_barrier(0);
; #pragma unroll
;                 for (int ks = 0; ks < 4; ++ks) { const bf16x8 vf = (bf16x8){lo[ks][0], lo[ks][1], lo[ks][2], lo[ks][3], hi[ks][0], hi[ks][1], hi[ks][2], hi[ks][3]};
;                     o[cb] = __builtin_amdgcn_mfma_f32_32x32x16_bf16(pa[ks], vf, o[cb], 0, 0, 0); }
;                 __builtin_amdgcn_sched_barrier(0); }
.Lfp_full:
	s_add_i32 s4, s86, 2
	s_cmp_gt_u32 s4, 2
	s_cselect_b32 s5, 3, 0
	s_sub_i32 s4, s4, s5
	s_mul_i32 s4, s4, 0xa100
	v_add3_u32 v210, s4, v149, v1
	v_add_u32_e32 v210, v210, v154
	ds_read_b64_tr_b16 v[82:83], v210 offset:8192
	ds_read_b64_tr_b16 v[84:85], v210 offset:8704
	ds_read_b64_tr_b16 v[86:87], v210 offset:9216
	ds_read_b64_tr_b16 v[88:89], v210 offset:9728
	ds_read_b64_tr_b16 v[90:91], v210 offset:10240
	ds_read_b64_tr_b16 v[92:93], v210 offset:10752
	ds_read_b64_tr_b16 v[94:95], v210 offset:11264
	ds_read_b64_tr_b16 v[96:97], v210 offset:11776
	ds_read_b64_tr_b16 v[112:113], v210 offset:12288
	ds_read_b64_tr_b16 v[114:115], v210 offset:12800
	ds_read_b64_tr_b16 v[116:117], v210 offset:13312
	ds_read_b64_tr_b16 v[118:119], v210 offset:13824
	ds_read_b64_tr_b16 v[120:121], v210 offset:14336
	ds_read_b64_tr_b16 v[122:123], v210 offset:14848
	ds_read_b64_tr_b16 v[124:125], v210 offset:15360
	ds_read_b64_tr_b16 v[126:127], v210 offset:15872
	s_add_i32 s6, s86, 1
	s_cmp_lg_u32 s86, 2
	s_cselect_b32 s6, s6, 0
	s_mul_i32 s6, s6, 0xa100
	v_lshlrev_b32_e32 v104, 7, v146
	v_add_u32_e32 v104, s6, v104
	v_add_u32_e32 v128, v104, v211
	v_add_u32_e32 v129, v104, v212
	v_add_u32_e32 v230, v104, v213
	v_add_u32_e32 v104, v104, v197
	v_readlane_b32 s5, v107, s87
	v_max3_f32 v216, v50, v51, v52
	v_max3_f32 v217, v34, v35, v36
	v_max3_f32 v216, v216, v53, v54
	v_max3_f32 v217, v217, v37, v38
	v_max3_f32 v216, v216, v55, v56
	v_max3_f32 v217, v217, v39, v40
	s_waitcnt lgkmcnt(14)
	v_mfma_f32_32x32x16_bf16 v[2:17], v[192:195], v[82:85], v[2:17]
	v_max3_f32 v216, v216, v57, v58
	v_max3_f32 v217, v217, v41, v42
	v_max3_f32 v216, v216, v59, v60
	v_max3_f32 v217, v217, v43, v44
	v_max3_f32 v216, v216, v61, v62
	v_max3_f32 v217, v217, v45, v46
	s_waitcnt lgkmcnt(12)
	v_mfma_f32_32x32x16_bf16 v[2:17], v[198:201], v[86:89], v[2:17]
	v_max3_f32 v216, v216, v63, v64
	v_max3_f32 v217, v217, v47, v48
	v_max_f32_e32 v216, v216, v65
	v_max_f32_e32 v217, v217, v49
	v_max_f32_e32 v216, v216, v217
	v_subrev_f32_e32 v231, s5, v109
	s_waitcnt lgkmcnt(10)
	v_mfma_f32_32x32x16_bf16 v[2:17], v[202:205], v[90:93], v[2:17]
	v_mov_b32_e32 v217, v216
	v_sub_f32_e32 v248, v111, v231
	v_add_f32_e32 v250, 0x40c00000, v248
	v_permlane32_swap_b32_e32 v216, v217
	v_max_f32_e32 v217, v217, v217
	s_waitcnt lgkmcnt(8)
	v_mfma_f32_32x32x16_bf16 v[2:17], v[206:209], v[94:97], v[2:17]
	v_max_f32_e32 v216, v216, v216
	v_max_f32_e32 v216, v216, v217
	v_cmp_gt_f32_e32 vcc, v216, v250
	s_cbranch_vccz .Lfp_ng_full
	s_nop 0
	v_cndmask_b32_e32 v249, v248, v216, vcc
	v_sub_f32_e32 v250, v248, v249
	v_exp_f32_e32 v250, v250
	v_add_f32_e32 v231, v231, v216
	v_cndmask_b32_e32 v111, v111, v231, vcc
	s_and_saveexec_b64 s[4:5], s[12:13]
	ds_write_b32 v108, v250
	s_or_b64 exec, exec, s[4:5]
	s_waitcnt lgkmcnt(0)
	v_mul_f32_e32 v110, v110, v250
	s_mov_b32 s100, 1
	s_branch .Lfp_gd_full

; #define LAS __attribute__((address_space(3)))
; template <int DQK, int DV, bool FOX> ...
;     ...
;             if (FOX) {
;                 const LAS float* ck = (const LAS float*)(b + KT_BYTES + VT_BYTES);
; #pragma unroll
;                 for (int g = 0; g < 4; ++g) { const f32x4 c0 = *(const LAS f32x4*)(ck + 8 * g + 4 * h), c1 = *(const LAS f32x4*)(ck + 32 + 8 * g + 4 * h);
; #pragma unroll
;                     for (int e = 0; e < 4; ++e) { p0[4 * g + e] = c0[e]; p1[4 * g + e] = c1[e]; } }
;             } else {
; #pragma unroll
;             for (int i = 0; i < 16; ++i) { p0[i] = 0.f; p1[i] = 0.f; }
;             }
;             {
;                 constexpr int GB = FOX ? 4 : 3;
; #pragma unroll
;                 for (int g0 = 0; g0 < ND0; g0 += GB) { bf16x8 ka[GB], kb[GB];
; #pragma unroll
;     ...
;             float ps = 0.f; f32x2v ps2 = {0.f, 0.f};
; #pragma unroll
;             for (int i = 0; i < 16; i += 2) { const f32x2v ml = (f32x2v){mloc, mloc};
;                 const f32x2v a0 = (f32x2v){p0[i], p0[i + 1]} - ml, a1 = (f32x2v){p1[i], p1[i + 1]} - ml;
;                 f32x2v e0, e1; e0.x = __builtin_amdgcn_exp2f(a0.x); e0.y = __builtin_amdgcn_exp2f(a0.y); e1.x = __builtin_amdgcn_exp2f(a1.x); e1.y = __builtin_amdgcn_exp2f(a1.y);
;                 p0[i] = e0.x; p0[i + 1] = e0.y; p1[i] = e1.x; p1[i + 1] = e1.y; ps2 += e0 + e1; }
;             ps = ps2.x + ps2.y;
;             lsum += ps;
;             bf16x8 pa[4];
;             { u32x4 t0, t1, t2, t3;
;               t0.x = pg8::cvt_pk_bf16(p0[0], p0[1]); t0.y = pg8::cvt_pk_bf16(p0[2], p0[3]); t0.z = pg8::cvt_pk_bf16(p0[4], p0[5]); t0.w = pg8::cvt_pk_bf16(p0[6], p0[7]);
;               t1.x = pg8::cvt_pk_bf16(p0[8], p0[9]); t1.y = pg8::cvt_pk_bf16(p0[10], p0[11]); t1.z = pg8::cvt_pk_bf16(p0[12], p0[13]); t1.w = pg8::cvt_pk_bf16(p0[14], p0[15]);
;               t2.x = pg8::cvt_pk_bf16(p1[0], p1[1]); t2.y = pg8::cvt_pk_bf16(p1[2], p1[3]); t2.z = pg8::cvt_pk_bf16(p1[4], p1[5]); t2.w = pg8::cvt_pk_bf16(p1[6], p1[7]);
;               t3.x = pg8::cvt_pk_bf16(p1[8], p1[9]); t3.y = pg8::cvt_pk_bf16(p1[10], p1[11]); t3.z = pg8::cvt_pk_bf16(p1[12], p1[13]); t3.w = pg8::cvt_pk_bf16(p1[14], p1[15]);
;               pa[0] = __builtin_bit_cast(bf16x8, t0); pa[1] = __builtin_bit_cast(bf16x8, t1); pa[2] = __builtin_bit_cast(bf16x8, t2); pa[3] = __builtin_bit_cast(bf16x8, t3); }
.Lfp_gd_full:
	ds_read_b128 v[82:85], v104
	ds_read_b128 v[90:93], v128
	ds_read_b128 v[86:89], v104 offset:4096
	ds_read_b128 v[94:97], v128 offset:4096
	v_sub_f32_e32 v130, v50, v249
	v_sub_f32_e32 v131, v51, v249
	v_sub_f32_e32 v132, v52, v249
	v_sub_f32_e32 v133, v53, v249
	v_exp_f32_e32 v130, v130
	v_exp_f32_e32 v131, v131
	v_exp_f32_e32 v132, v132
	v_exp_f32_e32 v133, v133
	s_waitcnt lgkmcnt(10)
	v_mfma_f32_32x32x16_bf16 v[18:33], v[192:195], v[112:115], v[18:33]
	v_sub_f32_e32 v134, v54, v249
	v_sub_f32_e32 v135, v55, v249
	v_sub_f32_e32 v136, v56, v249
	v_sub_f32_e32 v137, v57, v249
	v_exp_f32_e32 v134, v134
	v_exp_f32_e32 v135, v135
	v_exp_f32_e32 v136, v136
	v_exp_f32_e32 v137, v137
	s_waitcnt lgkmcnt(8)
	v_mfma_f32_32x32x16_bf16 v[18:33], v[198:201], v[116:119], v[18:33]
	ds_read_b128 v[112:115], v129
	ds_read_b128 v[116:119], v129 offset:4096
	v_sub_f32_e32 v138, v58, v249
	v_sub_f32_e32 v139, v59, v249
	v_sub_f32_e32 v140, v60, v249
	v_sub_f32_e32 v141, v61, v249
	v_exp_f32_e32 v138, v138
	v_exp_f32_e32 v139, v139
	v_exp_f32_e32 v140, v140
	v_exp_f32_e32 v141, v141
	s_waitcnt lgkmcnt(8)
	v_mfma_f32_32x32x16_bf16 v[18:33], v[202:205], v[120:123], v[18:33]
	v_sub_f32_e32 v142, v62, v249
	v_sub_f32_e32 v143, v63, v249
	v_sub_f32_e32 v144, v64, v249
	v_sub_f32_e32 v145, v65, v249
	v_exp_f32_e32 v142, v142
	v_exp_f32_e32 v143, v143
	v_exp_f32_e32 v144, v144
	v_exp_f32_e32 v145, v145
	s_waitcnt lgkmcnt(6)
	v_mfma_f32_32x32x16_bf16 v[18:33], v[206:209], v[124:127], v[18:33]
	v_lshl_add_u32 v214, v147, 2, s6
	ds_read_b128 v[50:53], v214 offset:16384
	ds_read_b128 v[54:57], v214 offset:16416
	ds_read_b128 v[58:61], v214 offset:16448
	ds_read_b128 v[62:65], v214 offset:16480
	ds_read_b128 v[120:123], v230
	ds_read_b128 v[124:127], v230 offset:4096
	v_sub_f32_e32 v232, v34, v249
	v_sub_f32_e32 v233, v35, v249
	v_sub_f32_e32 v234, v36, v249
	v_sub_f32_e32 v235, v37, v249
	v_exp_f32_e32 v232, v232
	v_exp_f32_e32 v233, v233
	v_exp_f32_e32 v234, v234
	v_exp_f32_e32 v235, v235
	v_sub_f32_e32 v236, v38, v249
	v_sub_f32_e32 v237, v39, v249
	v_sub_f32_e32 v238, v40, v249
	v_sub_f32_e32 v239, v41, v249
	v_exp_f32_e32 v236, v236
	v_exp_f32_e32 v237, v237
	s_waitcnt lgkmcnt(2)
	v_mfma_f32_32x32x16_bf16 v[50:65], v[82:85], v[66:69], v[50:65]
	v_exp_f32_e32 v238, v238
	v_exp_f32_e32 v239, v239
	v_sub_f32_e32 v240, v42, v249
	v_sub_f32_e32 v241, v43, v249
	v_sub_f32_e32 v242, v44, v249
	v_sub_f32_e32 v243, v45, v249
	s_waitcnt lgkmcnt(2)
	v_mfma_f32_32x32x16_bf16 v[50:65], v[90:93], v[70:73], v[50:65]
	v_exp_f32_e32 v240, v240
	v_exp_f32_e32 v241, v241
	v_exp_f32_e32 v242, v242
	v_exp_f32_e32 v243, v243
	v_sub_f32_e32 v244, v46, v249
	v_sub_f32_e32 v245, v47, v249
	s_waitcnt lgkmcnt(2)
	v_mfma_f32_32x32x16_bf16 v[50:65], v[112:115], v[74:77], v[50:65]
	v_sub_f32_e32 v246, v48, v249
	v_sub_f32_e32 v247, v49, v249
	v_exp_f32_e32 v244, v244
	v_exp_f32_e32 v245, v245
	v_exp_f32_e32 v246, v246
	v_exp_f32_e32 v247, v247
	s_waitcnt lgkmcnt(1)
	v_mfma_f32_32x32x16_bf16 v[50:65], v[120:123], v[78:81], v[50:65]
	ds_read_b128 v[34:37], v214 offset:16512
	ds_read_b128 v[38:41], v214 offset:16544
	ds_read_b128 v[42:45], v214 offset:16576
	ds_read_b128 v[46:49], v214 offset:16608
	v_add_f32_e32 v251, v130, v131
	v_add_f32_e32 v252, v138, v139
	v_add_f32_e32 v253, v232, v233
	v_add_f32_e32 v254, v240, v241
	v_add_f32_e32 v251, v251, v132
	v_add_f32_e32 v252, v252, v140
	v_add_f32_e32 v253, v253, v234
	v_add_f32_e32 v254, v254, v242
	v_add_f32_e32 v251, v251, v133
	v_add_f32_e32 v252, v252, v141
	v_add_f32_e32 v253, v253, v235
	v_add_f32_e32 v254, v254, v243
	s_waitcnt lgkmcnt(0)
	v_mfma_f32_32x32x16_bf16 v[34:49], v[86:89], v[66:69], v[34:49]
	v_add_f32_e32 v251, v251, v134
	v_add_f32_e32 v252, v252, v142
	v_add_f32_e32 v253, v253, v236
	v_add_f32_e32 v254, v254, v244
	v_add_f32_e32 v251, v251, v135
	v_add_f32_e32 v252, v252, v143
	v_add_f32_e32 v253, v253, v237
	v_add_f32_e32 v254, v254, v245
	v_add_f32_e32 v251, v251, v136
	v_add_f32_e32 v252, v252, v144
	v_mfma_f32_32x32x16_bf16 v[34:49], v[94:97], v[70:73], v[34:49]
	v_add_f32_e32 v253, v253, v238
	v_add_f32_e32 v254, v254, v246
	v_add_f32_e32 v251, v251, v137
	v_add_f32_e32 v252, v252, v145
	v_add_f32_e32 v253, v253, v239
	v_add_f32_e32 v254, v254, v247
	v_cvt_pk_bf16_f32 v192, v130, v131
	v_cvt_pk_bf16_f32 v193, v132, v133
	v_cvt_pk_bf16_f32 v194, v134, v135
	v_cvt_pk_bf16_f32 v195, v136, v137
	v_mfma_f32_32x32x16_bf16 v[34:49], v[116:119], v[74:77], v[34:49]
	v_add_f32_e32 v251, v251, v252
	v_cvt_pk_bf16_f32 v198, v138, v139
	v_cvt_pk_bf16_f32 v199, v140, v141
	v_cvt_pk_bf16_f32 v200, v142, v143
	v_cvt_pk_bf16_f32 v201, v144, v145
	v_add_f32_e32 v253, v253, v254
	v_cvt_pk_bf16_f32 v202, v232, v233
	v_cvt_pk_bf16_f32 v203, v234, v235
	v_cvt_pk_bf16_f32 v204, v236, v237
	v_cvt_pk_bf16_f32 v205, v238, v239
	v_mfma_f32_32x32x16_bf16 v[34:49], v[124:127], v[78:81], v[34:49]
	v_add_f32_e32 v251, v251, v253
	v_cvt_pk_bf16_f32 v206, v240, v241
	v_cvt_pk_bf16_f32 v207, v242, v243
	v_cvt_pk_bf16_f32 v208, v244, v245
	v_cvt_pk_bf16_f32 v209, v246, v247
	v_add_f32_e32 v110, v110, v251
	s_branch .Lfp_end
